# speedup vs baseline: 1.0067x; 1.0022x over previous
; __device__ __forceinline__ float siluf_(float x) { return x * __builtin_amdgcn_rcpf(1.0f + __builtin_amdgcn_exp2f(-1.4426950408889634f * x)); }
;     ...
;     } else if constexpr (EPI == EPI_SWIGLU) {
;       u16* Gp = (u16*)(ws + OFF_G);
; #pragma unroll
;       for (int m = 0; m < MT; ++m)
; #pragma unroll
;         for (int h = 0; h < 2; ++h) {
;           u32x2 pk;
;           pk.x = pack2(siluf_(acc[m][h][0]) * acc[m][2 + h][0], siluf_(acc[m][h][1]) * acc[m][2 + h][1]);
;           pk.y = pack2(siluf_(acc[m][h][2]) * acc[m][2 + h][2], siluf_(acc[m][h][3]) * acc[m][2 + h][3]);
;           *(u32x2*)(Gp + (size_t)(rbase + m * 16) * DFF + pn * 128 + wc * 32 + h * 16 + fq * 4) = pk;
;         }
.LBB0_182:
	v_mfma_f32_16x16x32_bf16 v[44:47], v[156:159], v[28:31], v[52:55]
	v_mfma_f32_16x16x32_bf16 v[52:55], v[160:163], v[28:31], v[168:171]
	v_mfma_f32_16x16x32_bf16 v[40:43], v[164:167], v[28:31], v[40:43]
	v_mfma_f32_16x16x32_bf16 v[36:39], v[152:155], v[176:179], v[36:39]
	v_mfma_f32_16x16x32_bf16 v[28:31], v[156:159], v[176:179], v[32:35]
	v_mfma_f32_16x16x32_bf16 v[32:35], v[160:163], v[176:179], v[172:175]
	v_mfma_f32_16x16x32_bf16 v[24:27], v[164:167], v[176:179], v[24:27]
	s_lshl_b32 s0, s25, 7
	s_ashr_i32 s1, s0, 31
	v_lshl_add_u32 v154, s50, 8, v223
	v_lshl_add_u64 v[152:153], s[0:1], 1, v[216:217]
	v_mad_i64_i32 v[156:157], s[0:1], v154, s53, v[152:153]
	s_mov_b32 s98, 0x16000
	s_mov_b32 s99, 0
	s_mov_b32 s100, 0xbfb8aa3b
	s_mov_b32 s101, 0xbfb8aa3b
	v_bfe_u32 v154, v228, 4, 1
	v_mul_u32_u24_e32 v154, 24, v154
	v_mov_b32_e32 v155, 0
	v_lshl_add_u64 v[156:157], v[156:157], 0, v[154:155]
	v_pk_mul_f32 v[152:153], v[144:145], s[100:101]
	v_pk_mul_f32 v[154:155], v[146:147], s[100:101]
	v_exp_f32_e32 v152, v152
	v_exp_f32_e32 v153, v153
	v_exp_f32_e32 v154, v154
	v_exp_f32_e32 v155, v155
	v_pk_add_f32 v[152:153], v[152:153], 1.0 op_sel_hi:[1,0]
	v_pk_add_f32 v[154:155], v[154:155], 1.0 op_sel_hi:[1,0]
	v_rcp_f32_e32 v152, v152
	v_rcp_f32_e32 v153, v153
	v_rcp_f32_e32 v154, v154
	v_rcp_f32_e32 v155, v155
	v_pk_mul_f32 v[144:145], v[144:145], v[152:153]
	v_pk_mul_f32 v[146:147], v[146:147], v[154:155]
	v_pk_mul_f32 v[144:145], v[144:145], v[148:149]
	v_pk_mul_f32 v[146:147], v[146:147], v[150:151]
	v_cvt_pk_bf16_f32 v144, v144, v145
	v_cvt_pk_bf16_f32 v145, v146, v147
	v_pk_mul_f32 v[152:153], v[140:141], s[100:101]
	v_pk_mul_f32 v[154:155], v[142:143], s[100:101]
	v_exp_f32_e32 v152, v152
	v_exp_f32_e32 v153, v153
	v_exp_f32_e32 v154, v154
	v_exp_f32_e32 v155, v155
	v_pk_add_f32 v[152:153], v[152:153], 1.0 op_sel_hi:[1,0]
	v_pk_add_f32 v[154:155], v[154:155], 1.0 op_sel_hi:[1,0]
	v_rcp_f32_e32 v152, v152
	v_rcp_f32_e32 v153, v153
	v_rcp_f32_e32 v154, v154
	v_rcp_f32_e32 v155, v155
	v_pk_mul_f32 v[140:141], v[140:141], v[152:153]
	v_pk_mul_f32 v[142:143], v[142:143], v[154:155]
	v_pk_mul_f32 v[140:141], v[140:141], v[136:137]
	v_pk_mul_f32 v[142:143], v[142:143], v[138:139]
	v_cvt_pk_bf16_f32 v146, v140, v141
	v_cvt_pk_bf16_f32 v147, v142, v143
	s_nop 1
	v_permlane16_swap_b32_e32 v144, v146
	v_permlane16_swap_b32_e32 v145, v147
	global_store_dwordx4 v[156:157], v[144:147], off
	v_lshl_add_u64 v[156:157], v[156:157], 0, s[98:99]
	v_pk_mul_f32 v[152:153], v[132:133], s[100:101]
	v_pk_mul_f32 v[154:155], v[134:135], s[100:101]
	v_exp_f32_e32 v152, v152
	v_exp_f32_e32 v153, v153
	v_exp_f32_e32 v154, v154
	v_exp_f32_e32 v155, v155
	v_pk_add_f32 v[152:153], v[152:153], 1.0 op_sel_hi:[1,0]
	v_pk_add_f32 v[154:155], v[154:155], 1.0 op_sel_hi:[1,0]
	v_rcp_f32_e32 v152, v152
	v_rcp_f32_e32 v153, v153
	v_rcp_f32_e32 v154, v154
	v_rcp_f32_e32 v155, v155
	v_pk_mul_f32 v[132:133], v[132:133], v[152:153]
	v_pk_mul_f32 v[134:135], v[134:135], v[154:155]
	v_pk_mul_f32 v[132:133], v[132:133], v[128:129]
	v_pk_mul_f32 v[134:135], v[134:135], v[130:131]
	v_cvt_pk_bf16_f32 v132, v132, v133
	v_cvt_pk_bf16_f32 v133, v134, v135
	v_pk_mul_f32 v[152:153], v[124:125], s[100:101]
	v_pk_mul_f32 v[154:155], v[126:127], s[100:101]
	v_exp_f32_e32 v152, v152
	v_exp_f32_e32 v153, v153
	v_exp_f32_e32 v154, v154
	v_exp_f32_e32 v155, v155
	v_pk_add_f32 v[152:153], v[152:153], 1.0 op_sel_hi:[1,0]
	v_pk_add_f32 v[154:155], v[154:155], 1.0 op_sel_hi:[1,0]
	v_rcp_f32_e32 v152, v152
	v_rcp_f32_e32 v153, v153
	v_rcp_f32_e32 v154, v154
	v_rcp_f32_e32 v155, v155
	v_pk_mul_f32 v[124:125], v[124:125], v[152:153]
	v_pk_mul_f32 v[126:127], v[126:127], v[154:155]
	v_pk_mul_f32 v[124:125], v[124:125], v[120:121]
	v_pk_mul_f32 v[126:127], v[126:127], v[122:123]
	v_cvt_pk_bf16_f32 v134, v124, v125
	v_cvt_pk_bf16_f32 v135, v126, v127
	s_nop 1
	v_permlane16_swap_b32_e32 v132, v134
	v_permlane16_swap_b32_e32 v133, v135
	global_store_dwordx4 v[156:157], v[132:135], off
	v_lshl_add_u64 v[156:157], v[156:157], 0, s[98:99]
	v_pk_mul_f32 v[152:153], v[112:113], s[100:101]
	v_pk_mul_f32 v[154:155], v[114:115], s[100:101]
	v_exp_f32_e32 v152, v152
	v_exp_f32_e32 v153, v153
	v_exp_f32_e32 v154, v154
	v_exp_f32_e32 v155, v155
	v_pk_add_f32 v[152:153], v[152:153], 1.0 op_sel_hi:[1,0]
	v_pk_add_f32 v[154:155], v[154:155], 1.0 op_sel_hi:[1,0]
	v_rcp_f32_e32 v152, v152
	v_rcp_f32_e32 v153, v153
	v_rcp_f32_e32 v154, v154
	v_rcp_f32_e32 v155, v155
	v_pk_mul_f32 v[112:113], v[112:113], v[152:153]
	v_pk_mul_f32 v[114:115], v[114:115], v[154:155]
	v_pk_mul_f32 v[112:113], v[112:113], v[116:117]
	v_pk_mul_f32 v[114:115], v[114:115], v[118:119]
	v_cvt_pk_bf16_f32 v112, v112, v113
	v_cvt_pk_bf16_f32 v113, v114, v115
	v_pk_mul_f32 v[152:153], v[108:109], s[100:101]
	v_pk_mul_f32 v[154:155], v[110:111], s[100:101]
	v_exp_f32_e32 v152, v152
	v_exp_f32_e32 v153, v153
	v_exp_f32_e32 v154, v154
	v_exp_f32_e32 v155, v155
	v_pk_add_f32 v[152:153], v[152:153], 1.0 op_sel_hi:[1,0]
	v_pk_add_f32 v[154:155], v[154:155], 1.0 op_sel_hi:[1,0]
	v_rcp_f32_e32 v152, v152
	v_rcp_f32_e32 v153, v153
	v_rcp_f32_e32 v154, v154
	v_rcp_f32_e32 v155, v155
	v_pk_mul_f32 v[108:109], v[108:109], v[152:153]
	v_pk_mul_f32 v[110:111], v[110:111], v[154:155]
	v_pk_mul_f32 v[108:109], v[108:109], v[104:105]
	v_pk_mul_f32 v[110:111], v[110:111], v[106:107]
	v_cvt_pk_bf16_f32 v114, v108, v109
	v_cvt_pk_bf16_f32 v115, v110, v111
	s_nop 1
	v_permlane16_swap_b32_e32 v112, v114
	v_permlane16_swap_b32_e32 v113, v115
	global_store_dwordx4 v[156:157], v[112:115], off
	v_lshl_add_u64 v[156:157], v[156:157], 0, s[98:99]
; __device__ __forceinline__ float siluf_(float x) { return x * __builtin_amdgcn_rcpf(1.0f + __builtin_amdgcn_exp2f(-1.4426950408889634f * x)); }
;     ...
;     } else if constexpr (EPI == EPI_SWIGLU) {
;       u16* Gp = (u16*)(ws + OFF_G);
; #pragma unroll
;       for (int m = 0; m < MT; ++m)
; #pragma unroll
;         for (int h = 0; h < 2; ++h) {
;           u32x2 pk;
;           pk.x = pack2(siluf_(acc[m][h][0]) * acc[m][2 + h][0], siluf_(acc[m][h][1]) * acc[m][2 + h][1]);
;           pk.y = pack2(siluf_(acc[m][h][2]) * acc[m][2 + h][2], siluf_(acc[m][h][3]) * acc[m][2 + h][3]);
;           *(u32x2*)(Gp + (size_t)(rbase + m * 16) * DFF + pn * 128 + wc * 32 + h * 16 + fq * 4) = pk;
;         }
	v_pk_mul_f32 v[152:153], v[100:101], s[100:101]
	v_pk_mul_f32 v[154:155], v[102:103], s[100:101]
	v_exp_f32_e32 v152, v152
	v_exp_f32_e32 v153, v153
	v_exp_f32_e32 v154, v154
	v_exp_f32_e32 v155, v155
	v_pk_add_f32 v[152:153], v[152:153], 1.0 op_sel_hi:[1,0]
	v_pk_add_f32 v[154:155], v[154:155], 1.0 op_sel_hi:[1,0]
	v_rcp_f32_e32 v152, v152
	v_rcp_f32_e32 v153, v153
	v_rcp_f32_e32 v154, v154
	v_rcp_f32_e32 v155, v155
	v_pk_mul_f32 v[100:101], v[100:101], v[152:153]
	v_pk_mul_f32 v[102:103], v[102:103], v[154:155]
	v_pk_mul_f32 v[100:101], v[100:101], v[96:97]
	v_pk_mul_f32 v[102:103], v[102:103], v[98:99]
	v_cvt_pk_bf16_f32 v100, v100, v101
	v_cvt_pk_bf16_f32 v101, v102, v103
	v_pk_mul_f32 v[152:153], v[92:93], s[100:101]
	v_pk_mul_f32 v[154:155], v[94:95], s[100:101]
	v_exp_f32_e32 v152, v152
	v_exp_f32_e32 v153, v153
	v_exp_f32_e32 v154, v154
	v_exp_f32_e32 v155, v155
	v_pk_add_f32 v[152:153], v[152:153], 1.0 op_sel_hi:[1,0]
	v_pk_add_f32 v[154:155], v[154:155], 1.0 op_sel_hi:[1,0]
	v_rcp_f32_e32 v152, v152
	v_rcp_f32_e32 v153, v153
	v_rcp_f32_e32 v154, v154
	v_rcp_f32_e32 v155, v155
	v_pk_mul_f32 v[92:93], v[92:93], v[152:153]
	v_pk_mul_f32 v[94:95], v[94:95], v[154:155]
	v_pk_mul_f32 v[92:93], v[92:93], v[88:89]
	v_pk_mul_f32 v[94:95], v[94:95], v[90:91]
	v_cvt_pk_bf16_f32 v102, v92, v93
	v_cvt_pk_bf16_f32 v103, v94, v95
	s_nop 1
	v_permlane16_swap_b32_e32 v100, v102
	v_permlane16_swap_b32_e32 v101, v103
	global_store_dwordx4 v[156:157], v[100:103], off
	v_lshl_add_u64 v[156:157], v[156:157], 0, s[98:99]
	v_pk_mul_f32 v[152:153], v[80:81], s[100:101]
	v_pk_mul_f32 v[154:155], v[82:83], s[100:101]
	v_exp_f32_e32 v152, v152
	v_exp_f32_e32 v153, v153
	v_exp_f32_e32 v154, v154
	v_exp_f32_e32 v155, v155
	v_pk_add_f32 v[152:153], v[152:153], 1.0 op_sel_hi:[1,0]
	v_pk_add_f32 v[154:155], v[154:155], 1.0 op_sel_hi:[1,0]
	v_rcp_f32_e32 v152, v152
	v_rcp_f32_e32 v153, v153
	v_rcp_f32_e32 v154, v154
	v_rcp_f32_e32 v155, v155
	v_pk_mul_f32 v[80:81], v[80:81], v[152:153]
	v_pk_mul_f32 v[82:83], v[82:83], v[154:155]
	v_pk_mul_f32 v[80:81], v[80:81], v[84:85]
	v_pk_mul_f32 v[82:83], v[82:83], v[86:87]
	v_cvt_pk_bf16_f32 v80, v80, v81
	v_cvt_pk_bf16_f32 v81, v82, v83
	v_pk_mul_f32 v[152:153], v[76:77], s[100:101]
	v_pk_mul_f32 v[154:155], v[78:79], s[100:101]
	v_exp_f32_e32 v152, v152
	v_exp_f32_e32 v153, v153
	v_exp_f32_e32 v154, v154
	v_exp_f32_e32 v155, v155
	v_pk_add_f32 v[152:153], v[152:153], 1.0 op_sel_hi:[1,0]
	v_pk_add_f32 v[154:155], v[154:155], 1.0 op_sel_hi:[1,0]
	v_rcp_f32_e32 v152, v152
	v_rcp_f32_e32 v153, v153
	v_rcp_f32_e32 v154, v154
	v_rcp_f32_e32 v155, v155
	v_pk_mul_f32 v[76:77], v[76:77], v[152:153]
	v_pk_mul_f32 v[78:79], v[78:79], v[154:155]
	v_pk_mul_f32 v[76:77], v[76:77], v[72:73]
	v_pk_mul_f32 v[78:79], v[78:79], v[74:75]
	v_cvt_pk_bf16_f32 v82, v76, v77
	v_cvt_pk_bf16_f32 v83, v78, v79
	s_nop 1
	v_permlane16_swap_b32_e32 v80, v82
	v_permlane16_swap_b32_e32 v81, v83
	global_store_dwordx4 v[156:157], v[80:83], off
	v_lshl_add_u64 v[156:157], v[156:157], 0, s[98:99]
	v_pk_mul_f32 v[152:153], v[68:69], s[100:101]
	v_pk_mul_f32 v[154:155], v[70:71], s[100:101]
	v_exp_f32_e32 v152, v152
	v_exp_f32_e32 v153, v153
	v_exp_f32_e32 v154, v154
	v_exp_f32_e32 v155, v155
	v_pk_add_f32 v[152:153], v[152:153], 1.0 op_sel_hi:[1,0]
	v_pk_add_f32 v[154:155], v[154:155], 1.0 op_sel_hi:[1,0]
	v_rcp_f32_e32 v152, v152
	v_rcp_f32_e32 v153, v153
	v_rcp_f32_e32 v154, v154
	v_rcp_f32_e32 v155, v155
	v_pk_mul_f32 v[68:69], v[68:69], v[152:153]
	v_pk_mul_f32 v[70:71], v[70:71], v[154:155]
	v_pk_mul_f32 v[68:69], v[68:69], v[64:65]
	v_pk_mul_f32 v[70:71], v[70:71], v[66:67]
	v_cvt_pk_bf16_f32 v68, v68, v69
	v_cvt_pk_bf16_f32 v69, v70, v71
	v_pk_mul_f32 v[152:153], v[60:61], s[100:101]
	v_pk_mul_f32 v[154:155], v[62:63], s[100:101]
	v_exp_f32_e32 v152, v152
	v_exp_f32_e32 v153, v153
	v_exp_f32_e32 v154, v154
	v_exp_f32_e32 v155, v155
	v_pk_add_f32 v[152:153], v[152:153], 1.0 op_sel_hi:[1,0]
; __device__ __forceinline__ float siluf_(float x) { return x * __builtin_amdgcn_rcpf(1.0f + __builtin_amdgcn_exp2f(-1.4426950408889634f * x)); }
; #define WAIT_V(n) asm volatile("s_waitcnt vmcnt(%0)" ::"n"(n) : "memory")
;     ...
;           if (q == 2 * NP - 1) {
;             WAIT_V(0);
;             __syncthreads();
;             if (more) {
;               if constexpr (BDBL) {
; #pragma unroll
;                 for (int n = 0; n < 4; ++n) Bq[0][n] = *(const bf16x8*)(sn + boff + (n * 2 + 0) * 1024);
;               }
; #pragma unroll
;               for (int i = 0; i < 2; ++i) Aq[0][i] = *(const bf16x8*)(sn + aoff + (i * 2 + 0) * 1024);
;             }
;     ...
;     } else if constexpr (EPI == EPI_SWIGLU) {
;       u16* Gp = (u16*)(ws + OFF_G);
; #pragma unroll
;       for (int m = 0; m < MT; ++m)
; #pragma unroll
;         for (int h = 0; h < 2; ++h) {
;           u32x2 pk;
;           pk.x = pack2(siluf_(acc[m][h][0]) * acc[m][2 + h][0], siluf_(acc[m][h][1]) * acc[m][2 + h][1]);
;           pk.y = pack2(siluf_(acc[m][h][2]) * acc[m][2 + h][2], siluf_(acc[m][h][3]) * acc[m][2 + h][3]);
;           *(u32x2*)(Gp + (size_t)(rbase + m * 16) * DFF + pn * 128 + wc * 32 + h * 16 + fq * 4) = pk;
;         }
	v_pk_add_f32 v[154:155], v[154:155], 1.0 op_sel_hi:[1,0]
	v_rcp_f32_e32 v152, v152
	v_rcp_f32_e32 v153, v153
	v_rcp_f32_e32 v154, v154
	v_rcp_f32_e32 v155, v155
	v_pk_mul_f32 v[60:61], v[60:61], v[152:153]
	v_pk_mul_f32 v[62:63], v[62:63], v[154:155]
	v_pk_mul_f32 v[60:61], v[60:61], v[56:57]
	v_pk_mul_f32 v[62:63], v[62:63], v[58:59]
	v_cvt_pk_bf16_f32 v70, v60, v61
	v_cvt_pk_bf16_f32 v71, v62, v63
	s_nop 1
	v_permlane16_swap_b32_e32 v68, v70
	v_permlane16_swap_b32_e32 v69, v71
	global_store_dwordx4 v[156:157], v[68:71], off
	v_lshl_add_u64 v[156:157], v[156:157], 0, s[98:99]
	v_pk_mul_f32 v[152:153], v[48:49], s[100:101]
	v_pk_mul_f32 v[154:155], v[50:51], s[100:101]
	v_exp_f32_e32 v152, v152
	v_exp_f32_e32 v153, v153
	v_exp_f32_e32 v154, v154
	v_exp_f32_e32 v155, v155
	v_pk_add_f32 v[152:153], v[152:153], 1.0 op_sel_hi:[1,0]
	v_pk_add_f32 v[154:155], v[154:155], 1.0 op_sel_hi:[1,0]
	v_rcp_f32_e32 v152, v152
	v_rcp_f32_e32 v153, v153
	v_rcp_f32_e32 v154, v154
	v_rcp_f32_e32 v155, v155
	v_pk_mul_f32 v[48:49], v[48:49], v[152:153]
	v_pk_mul_f32 v[50:51], v[50:51], v[154:155]
	v_pk_mul_f32 v[48:49], v[48:49], v[52:53]
	v_pk_mul_f32 v[50:51], v[50:51], v[54:55]
	v_cvt_pk_bf16_f32 v48, v48, v49
	v_cvt_pk_bf16_f32 v49, v50, v51
	v_pk_mul_f32 v[152:153], v[44:45], s[100:101]
	v_pk_mul_f32 v[154:155], v[46:47], s[100:101]
	v_exp_f32_e32 v152, v152
	v_exp_f32_e32 v153, v153
	v_exp_f32_e32 v154, v154
	v_exp_f32_e32 v155, v155
	v_pk_add_f32 v[152:153], v[152:153], 1.0 op_sel_hi:[1,0]
	v_pk_add_f32 v[154:155], v[154:155], 1.0 op_sel_hi:[1,0]
	v_rcp_f32_e32 v152, v152
	v_rcp_f32_e32 v153, v153
	v_rcp_f32_e32 v154, v154
	v_rcp_f32_e32 v155, v155
	v_pk_mul_f32 v[44:45], v[44:45], v[152:153]
	v_pk_mul_f32 v[46:47], v[46:47], v[154:155]
	v_pk_mul_f32 v[44:45], v[44:45], v[40:41]
	v_pk_mul_f32 v[46:47], v[46:47], v[42:43]
	v_cvt_pk_bf16_f32 v50, v44, v45
	v_cvt_pk_bf16_f32 v51, v46, v47
	s_nop 1
	v_permlane16_swap_b32_e32 v48, v50
	v_permlane16_swap_b32_e32 v49, v51
	global_store_dwordx4 v[156:157], v[48:51], off
	v_lshl_add_u64 v[156:157], v[156:157], 0, s[98:99]
	v_pk_mul_f32 v[152:153], v[36:37], s[100:101]
	v_pk_mul_f32 v[154:155], v[38:39], s[100:101]
	v_exp_f32_e32 v152, v152
	v_exp_f32_e32 v153, v153
	v_exp_f32_e32 v154, v154
	v_exp_f32_e32 v155, v155
	v_pk_add_f32 v[152:153], v[152:153], 1.0 op_sel_hi:[1,0]
	v_pk_add_f32 v[154:155], v[154:155], 1.0 op_sel_hi:[1,0]
	v_rcp_f32_e32 v152, v152
	v_rcp_f32_e32 v153, v153
	v_rcp_f32_e32 v154, v154
	v_rcp_f32_e32 v155, v155
	v_pk_mul_f32 v[36:37], v[36:37], v[152:153]
	v_pk_mul_f32 v[38:39], v[38:39], v[154:155]
	v_pk_mul_f32 v[36:37], v[36:37], v[32:33]
	v_pk_mul_f32 v[38:39], v[38:39], v[34:35]
	v_cvt_pk_bf16_f32 v36, v36, v37
	v_cvt_pk_bf16_f32 v37, v38, v39
	v_pk_mul_f32 v[152:153], v[28:29], s[100:101]
	v_pk_mul_f32 v[154:155], v[30:31], s[100:101]
	v_exp_f32_e32 v152, v152
	v_exp_f32_e32 v153, v153
	v_exp_f32_e32 v154, v154
	v_exp_f32_e32 v155, v155
	v_pk_add_f32 v[152:153], v[152:153], 1.0 op_sel_hi:[1,0]
	v_pk_add_f32 v[154:155], v[154:155], 1.0 op_sel_hi:[1,0]
	v_rcp_f32_e32 v152, v152
	v_rcp_f32_e32 v153, v153
	v_rcp_f32_e32 v154, v154
	v_rcp_f32_e32 v155, v155
	v_pk_mul_f32 v[28:29], v[28:29], v[152:153]
	v_pk_mul_f32 v[30:31], v[30:31], v[154:155]
	v_pk_mul_f32 v[28:29], v[28:29], v[24:25]
	v_pk_mul_f32 v[30:31], v[30:31], v[26:27]
	v_cvt_pk_bf16_f32 v38, v28, v29
	v_cvt_pk_bf16_f32 v39, v30, v31
	s_nop 1
	v_permlane16_swap_b32_e32 v36, v38
	v_permlane16_swap_b32_e32 v37, v39
	global_store_dwordx4 v[156:157], v[36:39], off
	s_waitcnt vmcnt(8)
	s_barrier
	s_and_b64 vcc, exec, s[12:13]
	s_mov_b32 s50, s23
	s_mov_b32 s25, s21
	s_mov_b64 s[16:17], s[6:7]
	s_mov_b64 s[0:1], s[10:11]
	s_cbranch_vccnz .LBB0_191
	ds_read_b128 v[12:15], v221 offset:32768
	ds_read_b128 v[8:11], v221 offset:34816
	ds_read_b128 v[4:7], v221 offset:36864
	ds_read_b128 v[0:3], v221 offset:38912
	ds_read_b128 v[20:23], v220
	ds_read_b128 v[16:19], v220 offset:2048

; __device__ __forceinline__ void hgrn_phase(const Params& P, char* shm, int lbid) {
;     ...
;         const float4 gl = *(const float4*)(pb + PB_GL + (16 * w + quad * 4) * 4);
; #pragma unroll
;         for (int vt = 0; vt < 8; ++vt) {
;           const bf16x8 bv = *(const bf16x8*)(pb + PB_VT + (vt * 16 + fr) * TSTR + quad * 16);
;           f32x4 t = __builtin_amdgcn_mfma_f32_16x16x32_bf16(a, bv, Sacc[vt], 0, 0, 0);
;           t[0] *= gl.x; t[1] *= gl.y; t[2] *= gl.z; t[3] *= gl.w;
;           Sacc[vt] = t;
;         }
;       }
;       {
;         const int tt = w >> 2, vt0 = (w & 3) * 2;
;         bf16x8 qf[4];
; #pragma unroll
;         for (int ks = 0; ks < 4; ++ks) qf[ks] = *(const bf16x8*)(pb + PB_Q + (tt * 16 + fr) * QSTR + (ks * 32 + quad * 8) * 2);
;         f32x4 AT[2];
; #pragma unroll
;         for (int st = 0; st < 2; ++st) {
;           f32x4 acc = f32x4{0.f, 0.f, 0.f, 0.f};
; #pragma unroll
;           for (int ks = 0; ks < 4; ++ks) {
;             const bf16x8 kf = *(const bf16x8*)(pb + PB_K + (st * 16 + fr) * QSTR + (ks * 32 + quad * 8) * 2);
;             acc = __builtin_amdgcn_mfma_f32_16x16x32_bf16(kf, qf[ks], acc, 0, 0, 0);
;           }
;           const int tpos = tt * 16 + fr;
; #pragma unroll
;           for (int jj = 0; jj < 4; ++jj)
;             if (st * 16 + quad * 4 + jj > tpos) acc[jj] = 0.0f;
;           AT[st] = acc;
;         }
;         u32x4 ap;
;         ap.x = pack2(AT[0][0], AT[0][1]); ap.y = pack2(AT[0][2], AT[0][3]);
;         ap.z = pack2(AT[1][0], AT[1][1]); ap.w = pack2(AT[1][2], AT[1][3]);
;         const int r0 = HG_R0(c);
; #pragma unroll
;         for (int e = 0; e < 2; ++e) {
;           const int vt = vt0 + e;
;           f32x4 O = f32x4{0.f, 0.f, 0.f, 0.f};
; #pragma unroll
;           for (int ks = 0; ks < 4; ++ks) {
;             const bf16x8 sf = *(const bf16x8*)(sb + (vt * 16 + fr) * QSTR + (ks * 32 + quad * 8) * 2);
;             O = __builtin_amdgcn_mfma_f32_16x16x32_bf16(qf[ks], sf, O, 0, 0, 0);
;           }
;           const char* vp = pb + PB_VT + (vt * 16 + fr) * TSTR + quad * 8;
;           const u32x2 lo = *(const u32x2*)vp, hi = *(const u32x2*)(vp + 32);
;           u32x4 bp; bp.x = lo.x; bp.y = lo.y; bp.z = hi.x; bp.w = hi.y;
;           O = __builtin_amdgcn_mfma_f32_16x16x32_bf16(__builtin_bit_cast(bf16x8, ap), __builtin_bit_cast(bf16x8, bp), O, 0, 0, 0);
; #pragma unroll
.LBB0_926:
	s_nop 0
	s_nop 0
	s_nop 0
	s_nop 0
	s_waitcnt lgkmcnt(0)
	v_pk_mul_f32 v[24:25], v[64:65], v[8:9]
	v_pk_mul_f32 v[8:9], v[64:65], v[56:57]
	v_mov_b32_e32 v56, s75
	v_cndmask_b32_e64 v56, v52, v56, s[16:17]
	v_cndmask_b32_e64 v56, v56, v52, s[14:15]
	v_mov_b32_e32 v52, s75
	s_nop 0
	s_nop 0
	s_nop 0
	s_nop 0
	v_pk_mul_f32 v[26:27], v[66:67], v[10:11]
	v_pk_mul_f32 v[10:11], v[66:67], v[58:59]
	v_cndmask_b32_e64 v53, 0, v53, s[14:15]
	v_cndmask_b32_e64 v54, v54, 0, s[18:19]
	v_cndmask_b32_e64 v55, v55, 0, s[20:21]
	v_cndmask_b32_e64 v57, v60, v52, s[6:7]
	v_cndmask_b32_e64 v58, v61, 0, s[8:9]
	v_cndmask_b32_e64 v59, v62, 0, s[10:11]
	v_cndmask_b32_e64 v60, v63, 0, s[12:13]
	v_cvt_pk_bf16_f32 v52, v56, v53
	v_cvt_pk_bf16_f32 v53, v54, v55
	v_cvt_pk_bf16_f32 v54, v57, v58
	v_cvt_pk_bf16_f32 v55, v59, v60
	ds_read_b128 v[56:59], v75
	ds_read_b128 v[60:63], v75 offset:64
	s_waitcnt lgkmcnt(1)
	v_mfma_f32_16x16x32_bf16 v[56:59], v[48:51], v[56:59], 0
	s_nop 0
	s_nop 0
	s_nop 0
	s_nop 0
	v_add3_u32 v127, s74, v69, v90
	s_waitcnt lgkmcnt(0)
	v_mfma_f32_16x16x32_bf16 v[56:59], v[44:47], v[60:63], v[56:59]
	ds_read_b128 v[60:63], v75 offset:128
	v_pk_mul_f32 v[4:5], v[64:65], v[4:5]
	v_pk_mul_f32 v[12:13], v[64:65], v[12:13]
	s_waitcnt lgkmcnt(0)
	v_mfma_f32_16x16x32_bf16 v[56:59], v[40:43], v[60:63], v[56:59]
	ds_read_b128 v[60:63], v75 offset:192
	v_pk_mul_f32 v[16:17], v[64:65], v[16:17]
	v_pk_mul_f32 v[20:21], v[64:65], v[20:21]
	s_waitcnt lgkmcnt(0)
	v_mfma_f32_16x16x32_bf16 v[56:59], v[36:39], v[60:63], v[56:59]
	v_add_u32_e32 v60, 0x6800, v127
	ds_read2_b64 v[60:63], v60 offset0:128 offset1:132
	v_pk_mul_f32 v[28:29], v[64:65], v[28:29]
	s_waitcnt lgkmcnt(0)
	v_mfma_f32_16x16x32_bf16 v[56:59], v[52:55], v[60:63], v[56:59]
	v_add_u32_e32 v60, s5, v89
	v_ashrrev_i32_e32 v61, 31, v60
	v_add_u32_e32 v62, s5, v88
	v_lshlrev_b64 v[60:61], 11, v[60:61]
	v_ashrrev_i32_e32 v63, 31, v62
	v_lshl_add_u64 v[60:61], v[70:71], 0, v[60:61]
	v_lshlrev_b64 v[62:63], 11, v[62:63]
	s_nop 0
	global_store_dword v[60:61], v56, off
	v_lshl_add_u64 v[62:63], v[70:71], 0, v[62:63]
	v_add_u32_e32 v56, s5, v87
	global_store_dword v[62:63], v57, off
	v_ashrrev_i32_e32 v57, 31, v56
	v_lshlrev_b64 v[56:57], 11, v[56:57]
	v_pk_mul_f32 v[32:33], v[64:65], v[32:33]
	v_lshl_add_u64 v[64:65], v[70:71], 0, v[56:57]
	v_add_u32_e32 v56, s5, v86
	v_ashrrev_i32_e32 v57, 31, v56
	v_lshlrev_b64 v[56:57], 11, v[56:57]
	v_pk_mul_f32 v[6:7], v[66:67], v[6:7]
	v_pk_mul_f32 v[14:15], v[66:67], v[14:15]
	v_pk_mul_f32 v[18:19], v[66:67], v[18:19]
	v_pk_mul_f32 v[22:23], v[66:67], v[22:23]
	v_pk_mul_f32 v[30:31], v[66:67], v[30:31]
	v_pk_mul_f32 v[34:35], v[66:67], v[34:35]
	v_lshl_add_u64 v[66:67], v[70:71], 0, v[56:57]
	global_store_dword v[64:65], v58, off
	global_store_dword v[66:67], v59, off
	ds_read_b128 v[56:59], v75 offset:4352
	s_waitcnt lgkmcnt(0)
	v_mfma_f32_16x16x32_bf16 v[48:51], v[48:51], v[56:59], 0
	ds_read_b128 v[56:59], v75 offset:4416
	s_add_i32 s50, s50, 32
	s_sub_i32 s51, s51, 32
	s_waitcnt lgkmcnt(0)
	v_mfma_f32_16x16x32_bf16 v[44:47], v[44:47], v[56:59], v[48:51]
	s_nop 0
	s_nop 1
	ds_read_b128 v[48:51], v75 offset:4480
	s_nop 0
	s_nop 0
	s_waitcnt lgkmcnt(0)
	v_mfma_f32_16x16x32_bf16 v[40:43], v[40:43], v[48:51], v[44:47]
	s_nop 2
	ds_read_b128 v[44:47], v75 offset:4544
	s_cmpk_eq_i32 s50, 0x8c0
	s_waitcnt lgkmcnt(0)
	v_mfma_f32_16x16x32_bf16 v[36:39], v[36:39], v[44:47], v[40:43]
	s_nop 2
	v_add_u32_e32 v40, 0x7000, v127
	ds_read2_b64 v[40:43], v40 offset0:32 offset1:36
	s_waitcnt lgkmcnt(0)
	v_mfma_f32_16x16x32_bf16 v[36:39], v[52:55], v[40:43], v[36:39]
	s_nop 7
	global_store_dword v[60:61], v36, off offset:64
	global_store_dword v[62:63], v37, off offset:64
	global_store_dword v[64:65], v38, off offset:64
	global_store_dword v[66:67], v39, off offset:64
	s_barrier
	s_waitcnt vmcnt(9)
	v_mov_b32_e32 v125, v206
	v_mov_b32_e32 v124, v207
	v_mov_b32_e32 v123, v208
	v_mov_b32_e32 v121, v209
	v_mov_b32_e32 v120, v211
	v_mov_b32_e32 v119, v212
	v_mov_b32_e32 v122, v210
	v_mov_b32_e32 v118, v213
	s_cbranch_scc1 .LBB0_928
	s_mov_b32 s61, s4
	v_mov_b64_e32 v[36:37], v[4:5]
	v_mov_b64_e32 v[38:39], v[6:7]
	v_mov_b64_e32 v[40:41], v[12:13]
	v_mov_b64_e32 v[42:43], v[14:15]
	v_mov_b64_e32 v[44:45], v[16:17]
	v_mov_b64_e32 v[46:47], v[18:19]
	v_mov_b64_e32 v[48:49], v[20:21]
	v_mov_b64_e32 v[50:51], v[22:23]
	v_mov_b64_e32 v[52:53], v[24:25]
	v_mov_b64_e32 v[54:55], v[26:27]
	v_mov_b64_e32 v[56:57], v[28:29]
	v_mov_b64_e32 v[58:59], v[30:31]
	v_mov_b64_e32 v[60:61], v[32:33]
	v_mov_b64_e32 v[62:63], v[34:35]
	v_mov_b64_e32 v[64:65], v[8:9]
	v_mov_b64_e32 v[66:67], v[10:11]
	s_branch .LBB0_908
